# P2 units of single-batch groups dealt so each XCD half produces what its own P3 tasks read; P2->P3 seam = per-half arrive counter in same-XCC mode
# baseline (speedup 1.0000x reference)
; #define PG8_STAGE(bufoff, gbase, voff) do { _Pragma("unroll") for (int _i = 0; _i < 2; ++_i) \
;         __builtin_amdgcn_global_load_lds((const unsigned*)((const char*)(gbase) + (voff)[_i]), (PG8_LAS unsigned*)(lds + (bufoff) + ldsw + _i * 8192), 16, 0, 0); } while (0)
; #define PG8_WAIT_V(n) asm volatile("s_waitcnt vmcnt(" #n ")" ::: "memory")
; #define PG8_BAR __builtin_amdgcn_s_barrier()
; template <class Epi, class Sched, bool ALIGN_EPI = false, bool SP2 = false>
; __device__ __forceinline__ void gemm_phase(PG8_LAS unsigned char* lds, const Gemm g, const Sched& S, const Epi& E, volatile PG8_LAS unsigned* sw = nullptr) {
;     ...
;     for (int i = 0; i < 2; ++i) { int R, C; stage_rc(tid * 16 + i * 8192, R, C); const int Rb = Epi::PERM ? ((R & ~31) + perm32(R & 31)) : R;
;         const int Ra = Epi::PERMA ? ((R & 64) + 4 * (R & 15) + ((R >> 4) & 3)) : R;
;         voffA[i] = (unsigned)(Ra * BK + C) * 2u; voffB[i] = (unsigned)(Rb * BK + C) * 2u; }
;     const size_t kstep = (size_t)(BM * BK * 2);
;     const size_t hstep = (size_t)HALF * BK * 2;
;     const size_t tstep = (size_t)K * BM * 2;
;     const unsigned ldsw = (unsigned)wid * 1024u;
;     const int aoff = lds_byte(wr * 64 + fr, fq * 8), boff = lds_byte(wc * 32 + fr, fq * 8);
;     ...
;     const char* cA = (const char*)g.A + (size_t)cur.pm * tstep; const char* cB = (const char*)g.Bt + (size_t)cur.pn * tstep;
;     S.a_ready(cur);
;     if constexpr (SP2) {
;         PG8_STAGE(PG8_SB(0, 0), cB, voffB); PG8_STAGE(PG8_SB(0, 1), cB + hstep, voffB); PG8_STAGE(PG8_SA(0, 0), cA, voffA); PG8_STAGE(PG8_SA(0, 1), cA + hstep, voffA);
;         if (wr == 1) PG8_BAR;
;         PG8_WAIT_V(2); PG8_BAR;
;         PG8_STAGE(PG8_SB(1, 0), cB + kstep, voffB); PG8_STAGE(PG8_SA(1, 0), cA + kstep, voffA); PG8_STAGE(PG8_SB(1, 1), cB + hstep + kstep, voffB);
.LBB0_153:
	v_writelane_b32 v250, s70, 40
	s_nop 1
	v_writelane_b32 v250, s71, 41
	v_writelane_b32 v250, s68, 42
	s_nop 1
	v_writelane_b32 v250, s69, 43
	s_or_b64 exec, exec, s[0:1]
	s_and_saveexec_b64 s[4:5], s[80:81]
	v_mov_b32_e32 v1, 0x18800
	global_load_dword v2, v1, s[60:61] sc1
	s_waitcnt vmcnt(0)
	v_readfirstlane_b32 s100, v2
	s_or_b64 exec, exec, s[4:5]
	v_readlane_b32 s3, v250, 10
	s_mul_i32 s0, s3, 0x7000000
	s_add_u32 s0, s60, s0
	s_addc_u32 s1, s61, 0
	s_add_u32 s16, s0, 0x2800000
	s_addc_u32 s17, s1, 0
	s_ashr_i32 s97, s2, 3
	s_and_b32 s18, s2, 1
	s_ashr_i32 s62, s83, 3
	s_add_u32 s91, s60, 0x100000
	s_addc_u32 s92, s61, 0
	s_add_u32 s24, s0, 0x3800000
	s_addc_u32 s25, s1, 0
	s_lshl_b32 s60, s18, 4
	s_lshl_b32 s61, s3, 13
	v_mov_b32_e32 v2, v0
	s_waitcnt lgkmcnt(0)
	s_barrier
	s_cmpk_lt_i32 s97, 0x80
	s_nop 0
	v_readfirstlane_b32 s6, v2
	s_cbranch_scc0 .LBB0_173
	v_lshlrev_b32_e32 v1, 4, v2
	v_add_u32_e32 v4, 0x2000, v1
	v_ashrrev_i32_e32 v3, 31, v4
	v_lshrrev_b32_e32 v3, 22, v3
	v_add_u32_e32 v3, v4, v3
	v_ashrrev_i32_e32 v3, 10, v3
	v_mul_i32_i24_e32 v5, 0x400, v3
	v_sub_u32_e32 v4, v4, v5
	v_lshrrev_b32_e32 v5, 4, v4
	v_bitop3_b32 v5, v5, v4, 32 bitop3:0x6c
	v_ashrrev_i32_e32 v4, 31, v5
	v_lshrrev_b32_e32 v4, 26, v4
	v_add_u32_e32 v6, v5, v4
	v_lshlrev_b32_e32 v7, 3, v3
	v_ashrrev_i32_e32 v4, 6, v6
	v_and_b32_e32 v7, -16, v7
	v_add_u32_e32 v7, v4, v7
	v_and_b32_e32 v8, 3, v4
	s_mov_b32 s8, 0x1ffffe0
	v_lshrrev_b32_e32 v9, 2, v7
	v_lshlrev_b32_e32 v10, 1, v7
	v_and_or_b32 v8, v7, s8, v8
	v_and_b32_e32 v9, 4, v9
	v_and_b32_e32 v10, 24, v10
	v_and_b32_e32 v6, 0xc0, v6
	v_or3_b32 v8, v8, v9, v10
	v_sub_u32_e32 v5, v5, v6
	v_mov_b32_e32 v10, 1
	v_lshlrev_b32_e32 v9, 5, v3
	v_ashrrev_i16_sdwa v5, v10, sext(v5) dst_sel:DWORD dst_unused:UNUSED_PAD src0_sel:DWORD src1_sel:BYTE_0
	v_and_b32_e32 v9, 32, v9
	v_bfe_i32 v5, v5, 0, 16
	s_ashr_i32 s0, s97, 31
	v_add_lshl_u32 v6, v9, v5, 1
	s_lshr_b32 s0, s0, 26
	v_lshl_add_u32 v130, v8, 7, v6
	v_lshl_add_u32 v132, v7, 7, v6
	v_bfe_i32 v6, v2, 27, 1
	s_add_i32 s0, s97, s0
	v_lshrrev_b32_e32 v6, 22, v6
	s_ashr_i32 s1, s0, 6
	s_andn2_b32 s0, s0, 63
	v_add_u32_e32 v6, v1, v6
	s_sub_i32 s0, s97, s0
	s_lshl_b32 s1, s1, 3
	v_and_b32_e32 v6, 0xfffffc00, v6
	s_add_i32 s1, s1, s60
	s_and_b32 s2, s0, 7
	v_sub_u32_e32 v1, v1, v6
	s_or_b32 s46, s1, s2
	s_ashr_i32 s2, s0, 3
	s_bitcmp1_b32 s101, 2
	s_cbranch_scc0 .Lp2map_skip0
	s_and_b32 s0, s101, 1
	s_lshr_b32 s1, s97, 5
	s_bfe_u32 s3, s97, 0x20003
	s_and_b32 s46, s97, 7
	s_and_b32 s4, s1, 1
	s_lshl_b32 s4, s4, 3
	s_add_i32 s46, s46, s4
	s_lshr_b32 s1, s1, 1
	s_cmp_lt_u32 s3, 3
	s_cselect_b32 s4, 1, 0
	s_and_b32 s5, s1, s4
	s_xor_b32 s5, s5, s0
	s_lshl_b32 s5, s5, 4
	s_add_i32 s46, s46, s5
	s_lshl_b32 s2, s3, 1
	s_add_i32 s2, s2, s0
	s_add_i32 s1, s1, 6
	s_cmp_eq_u32 s4, 1
	s_cselect_b32 s2, s2, s1
.Lp2map_skip0:
	v_lshrrev_b32_e32 v6, 4, v1
	v_ashrrev_i32_e32 v7, 31, v2
	s_ashr_i32 s47, s46, 31
	s_ashr_i32 s3, s2, 31
	v_bitop3_b32 v1, v6, v1, 32 bitop3:0x6c
	v_lshrrev_b32_e32 v7, 26, v7
	s_lshl_b64 s[0:1], s[46:47], 19
	s_lshl_b64 s[4:5], s[2:3], 19
	v_ashrrev_i32_e32 v6, 31, v1
	v_add_u32_e32 v7, v2, v7
	s_add_u32 s50, s14, s4
	v_lshrrev_b32_e32 v6, 26, v6
	v_ashrrev_i32_e32 v7, 6, v7
	s_addc_u32 s51, s15, s5
	v_add_u32_e32 v8, v1, v6
	v_lshlrev_b32_e32 v9, 3, v7
	s_add_u32 s48, s16, s0
	v_ashrrev_i32_e32 v6, 6, v8
	v_and_b32_e32 v9, -16, v9
	s_addc_u32 s49, s17, s1
	s_ashr_i32 s3, s6, 6
	v_add_u32_e32 v9, v6, v9
	s_ashr_i32 s7, s6, 8
	s_lshl_b32 s19, s3, 10
	v_and_b32_e32 v11, 3, v6
	v_lshrrev_b32_e32 v12, 2, v9
	v_lshlrev_b32_e32 v13, 1, v9
	v_and_b32_e32 v8, 0xc0, v8
	s_add_u32 s0, s48, 0x4000
	v_and_or_b32 v11, v9, s8, v11
	v_and_b32_e32 v12, 4, v12
	v_and_b32_e32 v13, 24, v13
	v_sub_u32_e32 v1, v1, v8
	s_addc_u32 s1, s49, 0
	v_or3_b32 v11, v11, v12, v13
	v_lshlrev_b32_e32 v12, 5, v7
	v_ashrrev_i16_sdwa v1, v10, sext(v1) dst_sel:DWORD dst_unused:UNUSED_PAD src0_sel:DWORD src1_sel:BYTE_0
	s_add_u32 s4, s50, 0x4000
	v_and_b32_e32 v12, 32, v12
	v_bfe_i32 v8, v1, 0, 16
	s_addc_u32 s5, s51, 0
	v_add_lshl_u32 v1, v12, v8, 1
	s_add_i32 s20, s19, 0
	v_lshl_add_u32 v134, v11, 7, v1
	s_add_i32 m0, s20, 0x10000
	v_lshl_add_u32 v136, v9, 7, v1
	global_load_lds_dwordx4 v134, s[50:51]
	s_add_i32 m0, s20, 0x12000
	s_add_i32 s21, s20, 0x2000
	global_load_lds_dwordx4 v130, s[50:51]
	s_add_i32 m0, s20, 0x14000
	s_add_i32 s22, s20, 0x4000
	global_load_lds_dwordx4 v134, s[4:5]
	s_add_i32 m0, s20, 0x16000
	s_add_i32 s23, s20, 0x6000
	global_load_lds_dwordx4 v130, s[4:5]
	s_mov_b32 m0, s20
	v_mov_b32_e32 v135, 0
	global_load_lds_dwordx4 v136, s[48:49]
	s_mov_b32 m0, s21
	s_cmp_eq_u32 s7, 1
	global_load_lds_dwordx4 v132, s[48:49]
	s_mov_b32 m0, s22
	v_mov_b32_e32 v131, v135
	global_load_lds_dwordx4 v136, s[0:1]
	s_mov_b32 m0, s23
	v_mov_b32_e32 v137, v135
	global_load_lds_dwordx4 v132, s[0:1]
	s_cselect_b64 s[4:5], -1, 0
	s_cmp_lg_u32 s7, 1
	v_mov_b32_e32 v133, v135
	s_cbranch_scc1 .LBB0_156
	s_barrier

;     __device__ bool next(int i, pg8::Unit& u) const { const int L = i * cph + k; if (L >= nunits) return false; const int nig = 8 * nN, gid = L / nig, w = L % nig; u.pm = 16 * xh + 8 * gid + (w & 7); u.pn = w >> 3; return true; }
; template <class Epi, class Sched, bool ALIGN_EPI = false, bool SP2 = false>
; __device__ __forceinline__ void gemm_phase(PG8_LAS unsigned char* lds, const Gemm g, const Sched& S, const Epi& E, volatile PG8_LAS unsigned* sw = nullptr) {
;     ...
;         const bool has_next = S.next(ui + 1, nxt);
;         const char* nA = has_next ? (const char*)g.A + (size_t)nxt.pm * tstep : cA; const char* nB = has_next ? (const char*)g.Bt + (size_t)nxt.pn * tstep : cB;
;     ...
; #pragma unroll
;         for (int a = 0; a < 2; ++a)
; #pragma unroll
;             for (int b = 0; b < 2; ++b)
; #pragma unroll
;                 for (int m = 0; m < 4; ++m)
; #pragma unroll
;                     for (int n = 0; n < 2; ++n) acc[a][b][m][n] = (f32x4){0.f, 0.f, 0.f, 0.f};
;         cur = nxt; cA = nA; cB = nB; ++ui;
.LBB0_159:
	s_add_i32 s43, s43, 1
	s_mul_i32 s3, s43, s62
	s_add_i32 s3, s3, s97
	s_cmpk_lt_i32 s3, 0x80
	s_cselect_b64 s[28:29], -1, 0
	s_cmpk_gt_i32 s3, 0x7f
	s_cbranch_scc1 .LBB0_161
	s_ashr_i32 s10, s3, 31
	s_lshr_b32 s10, s10, 26
	s_add_i32 s10, s3, s10
	s_ashr_i32 s11, s10, 6
	s_andn2_b32 s10, s10, 63
	s_sub_i32 s3, s3, s10
	s_lshl_b32 s10, s11, 3
	s_add_i32 s10, s10, s60
	s_and_b32 s11, s3, 7
	s_or_b32 s10, s10, s11
	s_ashr_i32 s12, s3, 3
	s_bitcmp1_b32 s101, 2
	s_cbranch_scc0 .Lp2map_skip1
	s_mul_i32 s3, s43, s62
	s_add_i32 s3, s3, s97
	s_and_b32 s11, s101, 1
	s_lshr_b32 s13, s3, 5
	s_bfe_u32 s26, s3, 0x20003
	s_and_b32 s10, s3, 7
	s_and_b32 s27, s13, 1
	s_lshl_b32 s27, s27, 3
	s_add_i32 s10, s10, s27
	s_lshr_b32 s13, s13, 1
	s_cmp_lt_u32 s26, 3
	s_cselect_b32 s27, 1, 0
	s_and_b32 s30, s13, s27
	s_xor_b32 s30, s30, s11
	s_lshl_b32 s30, s30, 4
	s_add_i32 s10, s10, s30
	s_lshl_b32 s12, s26, 1
	s_add_i32 s12, s12, s11
	s_add_i32 s13, s13, 6
	s_cmp_eq_u32 s27, 1
	s_cselect_b32 s12, s12, s13
.Lp2map_skip1:
.LBB0_161:
	s_ashr_i32 s11, s10, 31
	s_lshl_b64 s[26:27], s[10:11], 19
	s_add_u32 s26, s16, s26
	s_addc_u32 s27, s17, s27
	s_and_b64 s[30:31], s[28:29], exec
	s_cselect_b32 s3, s27, s49
	s_cselect_b32 s11, s26, s48
	s_ashr_i32 s13, s12, 31
	s_lshl_b64 s[30:31], s[12:13], 19
	s_add_u32 s30, s14, s30
	s_addc_u32 s31, s15, s31
	s_and_b64 s[52:53], s[28:29], exec
	s_cselect_b32 s13, s31, s51
	s_cselect_b32 s47, s30, s50
	s_add_u32 s48, s48, 0xc000
	s_addc_u32 s49, s49, 0
	s_add_u32 s59, s50, 0x10000
	v_mov_b32_e32 v2, 0
	s_addc_u32 s64, s51, 0
	s_mov_b32 s65, -2
	v_mov_b32_e32 v3, v2
	v_mov_b32_e32 v4, v2
	v_mov_b32_e32 v5, v2
	v_mov_b32_e32 v6, v2
	v_mov_b32_e32 v7, v2
	v_mov_b32_e32 v8, v2
	v_mov_b32_e32 v9, v2
	v_mov_b32_e32 v10, v2
	v_mov_b32_e32 v11, v2
	v_mov_b32_e32 v12, v2
	v_mov_b32_e32 v13, v2
	v_mov_b32_e32 v18, v2
	v_mov_b32_e32 v19, v2
	v_mov_b32_e32 v20, v2
	v_mov_b32_e32 v21, v2
	v_mov_b32_e32 v26, v2
	v_mov_b32_e32 v27, v2
	v_mov_b32_e32 v28, v2
	v_mov_b32_e32 v29, v2
	v_mov_b32_e32 v34, v2
	v_mov_b32_e32 v35, v2
	v_mov_b32_e32 v36, v2
	v_mov_b32_e32 v37, v2
	v_mov_b32_e32 v42, v2
	v_mov_b32_e32 v43, v2
	v_mov_b32_e32 v44, v2
	v_mov_b32_e32 v45, v2
	v_mov_b32_e32 v50, v2
	v_mov_b32_e32 v51, v2
	v_mov_b32_e32 v52, v2
	v_mov_b32_e32 v53, v2
	v_mov_b32_e32 v14, v2
	v_mov_b32_e32 v15, v2
	v_mov_b32_e32 v16, v2
	v_mov_b32_e32 v17, v2
	v_mov_b32_e32 v22, v2
	v_mov_b32_e32 v23, v2
	v_mov_b32_e32 v24, v2
	v_mov_b32_e32 v25, v2
	v_mov_b32_e32 v30, v2
	v_mov_b32_e32 v31, v2
	v_mov_b32_e32 v32, v2
	v_mov_b32_e32 v33, v2
	v_mov_b32_e32 v38, v2
	v_mov_b32_e32 v39, v2
	v_mov_b32_e32 v40, v2
	v_mov_b32_e32 v41, v2
	v_mov_b32_e32 v46, v2
	v_mov_b32_e32 v47, v2
	v_mov_b32_e32 v48, v2
	v_mov_b32_e32 v49, v2
	v_mov_b32_e32 v54, v2
	v_mov_b32_e32 v55, v2
	v_mov_b32_e32 v56, v2
	v_mov_b32_e32 v57, v2
	v_mov_b32_e32 v58, v2
	v_mov_b32_e32 v59, v2
	v_mov_b32_e32 v60, v2
	v_mov_b32_e32 v61, v2
	v_mov_b32_e32 v62, v2
	v_mov_b32_e32 v63, v2
	v_mov_b32_e32 v64, v2
	v_mov_b32_e32 v65, v2
	v_mov_b32_e32 v66, v2
	v_mov_b32_e32 v67, v2
	v_mov_b32_e32 v68, v2
	v_mov_b32_e32 v69, v2
	v_mov_b32_e32 v70, v2
	v_mov_b32_e32 v71, v2
	v_mov_b32_e32 v72, v2
	v_mov_b32_e32 v73, v2
	v_mov_b32_e32 v74, v2
	v_mov_b32_e32 v75, v2
	v_mov_b32_e32 v76, v2
	v_mov_b32_e32 v77, v2
	v_mov_b32_e32 v82, v2
	v_mov_b32_e32 v83, v2
	v_mov_b32_e32 v84, v2
	v_mov_b32_e32 v85, v2
	v_mov_b32_e32 v90, v2
	v_mov_b32_e32 v91, v2
	v_mov_b32_e32 v92, v2
	v_mov_b32_e32 v93, v2
	v_mov_b32_e32 v98, v2
	v_mov_b32_e32 v99, v2
	v_mov_b32_e32 v100, v2
	v_mov_b32_e32 v101, v2
	v_mov_b32_e32 v106, v2
	v_mov_b32_e32 v107, v2
	v_mov_b32_e32 v108, v2
	v_mov_b32_e32 v109, v2
	v_mov_b32_e32 v114, v2
	v_mov_b32_e32 v115, v2
	v_mov_b32_e32 v116, v2
	v_mov_b32_e32 v117, v2
	v_mov_b32_e32 v78, v2
	v_mov_b32_e32 v79, v2
	v_mov_b32_e32 v80, v2
	v_mov_b32_e32 v81, v2
	v_mov_b32_e32 v86, v2
	v_mov_b32_e32 v87, v2
	v_mov_b32_e32 v88, v2
	v_mov_b32_e32 v89, v2
	v_mov_b32_e32 v94, v2
	v_mov_b32_e32 v95, v2
	v_mov_b32_e32 v96, v2
	v_mov_b32_e32 v97, v2
	v_mov_b32_e32 v102, v2
	v_mov_b32_e32 v103, v2
	v_mov_b32_e32 v104, v2
	v_mov_b32_e32 v105, v2
	v_mov_b32_e32 v110, v2
	v_mov_b32_e32 v111, v2
	v_mov_b32_e32 v112, v2
	v_mov_b32_e32 v113, v2
	v_mov_b32_e32 v118, v2
	v_mov_b32_e32 v119, v2
	v_mov_b32_e32 v120, v2
	v_mov_b32_e32 v121, v2
	v_mov_b32_e32 v122, v2
	v_mov_b32_e32 v123, v2
	v_mov_b32_e32 v124, v2
	v_mov_b32_e32 v125, v2
	v_mov_b32_e32 v126, v2
	v_mov_b32_e32 v127, v2
	v_mov_b32_e32 v128, v2
	v_mov_b32_e32 v129, v2

; #define PG8_WAIT_V(n) asm volatile("s_waitcnt vmcnt(" #n ")" ::: "memory")
; #define PG8_BAR __builtin_amdgcn_s_barrier()
; #define SEAM(k) do { if ((k) < 2) xcd_barrier(bar); else xcd_barrier(barg); } while (0)
; template <class Epi, class Sched, bool ALIGN_EPI = false, bool SP2 = false>
; __device__ __forceinline__ void gemm_phase(PG8_LAS unsigned char* lds, const Gemm g, const Sched& S, const Epi& E, volatile PG8_LAS unsigned* sw = nullptr) {
;     ...
;     PG8_WAIT_V(0);
;     if constexpr (!ALIGN_EPI) { if (wr == 0) PG8_BAR; }
;     PG8_BAR;
; __global__ void __launch_bounds__(NWAVES * 64, 2) fwd(Args a) {
;     ...
;     SEAM(2);
.LBB0_173:
	s_waitcnt vmcnt(0)
	s_ashr_i32 s19, s83, 2
	s_waitcnt vmcnt(0)
	s_barrier
	s_and_saveexec_b64 s[0:1], s[80:81]
	s_xor_b64 s[0:1], exec, s[0:1]
	s_cbranch_execz .LBB0_226
	s_cmp_lg_u32 s100, 0
	s_cbranch_scc1 .Lq2_slow
	v_readlane_b32 s4, v250, 14
	v_readlane_b32 s5, v250, 15
	s_and_b32 s6, s101, 7
	s_lshl_b32 s6, s6, 7
	s_add_i32 s6, s6, 0x18c00
	v_mov_b32_e32 v1, s6
	v_mov_b32_e32 v2, 1
	s_mov_b32 s9, 0
	s_nop 4
	global_atomic_add v1, v2, s[4:5]
	buffer_inv sc1

; __device__ __forceinline__ unsigned xb_ld(unsigned* p)              { return __hip_atomic_load(p, __ATOMIC_RELAXED, __HIP_MEMORY_SCOPE_AGENT); }
; __device__ __forceinline__ void xcd_barrier_complete(unsigned* bar, unsigned x, unsigned G, unsigned& nloc, unsigned& nx) {
;     unsigned sum, cnt, mine, sp = 0u;
;     for (;;) {
;         sum = 0u; cnt = 0u; mine = 0u;
; #pragma unroll
;         for (unsigned j = 0; j < 16; ++j) { const unsigned c = xb_ld(&bar[XB_XCNT(j)]); sum += c; cnt += (c > 0u) ? 1u : 0u; mine = (j == x) ? c : mine; }
; __device__ __forceinline__ void xcd_barrier(const XcdBarrier& b) {
;     ...
;         unsigned nloc = b.st[0], nx = b.st[1];
;         if (nloc == 0u) { xcd_barrier_complete(bar, b.x, b.gsize, nloc, nx); b.st[0] = nloc; b.st[1] = nx; }
.Lq2_slow:
	s_add_i32 s2, 0, 0x26170
	v_mov_b32_e32 v1, s2
	s_waitcnt vmcnt(0) expcnt(0) lgkmcnt(0)
	ds_read_b32 v3, v1
	s_add_i32 s2, 0, 0x26174
	v_mov_b32_e32 v1, s2
	ds_read_b32 v1, v1
	s_waitcnt lgkmcnt(1)
	v_cmp_ne_u32_e32 vcc, 0, v3
	s_cbranch_vccnz .LBB0_189
	s_add_u32 s2, s34, 0x1000
	s_addc_u32 s3, s35, 0
	s_add_u32 s4, s34, 0x1100
	s_addc_u32 s5, s35, 0
	s_add_u32 s6, s34, 0x1200
	s_addc_u32 s7, s35, 0
	s_add_u32 s8, s34, 0x1300
	s_addc_u32 s9, s35, 0
	s_mov_b32 s14, 1
	v_mov_b32_e32 v17, 0
	s_branch .LBB0_177
